# combined variant + final-norm phase with batched loads
# speedup vs baseline: 1.0162x; 1.0162x over previous
; __device__ __forceinline__ float bf_lo(unsigned w) { return __uint_as_float(w << 16); }
; __device__ __forceinline__ float bf_hi(unsigned w) { return __uint_as_float(w & 0xffff0000u); }
; template <class T> __device__ __forceinline__ T* g_(T* p) { return (T*)(GAS T*)p; }
; __device__ __forceinline__ size_t oq(size_t c) { asm volatile("" : "+s"(c)); return c; }
; #define PHASE_IDS() const int tid = opaque_tid(), lane = tid & 63, wave = __builtin_amdgcn_readfirstlane(tid >> 6); (void)lane; (void)wave
; __device__ __forceinline__ void p_final(Frame& F) {
;     PHASE_IDS();
;     const bf16_t* HB = (const bf16_t*)(F.ws + oq(WS_HB)); const float* SS = (const float*)(F.ws + oq(WS_SS)); const float* nf = g_(F.in[19]);
;     const int gw = F.vcu * NWAVES + wave, NGW = F.G * NWAVES;
;     for (int m = gw; m < MROWS; m += NGW) {
;         float s = 0.f;
; #pragma unroll
;         for (int j = 0; j < 8; ++j) s += SS[(size_t)j * MROWS + m];
;         const float rstd = __builtin_amdgcn_rsqf(s * (1.0f / DM) + EPS);
;         const u32x4* hr = (const u32x4*)(HB + (size_t)m * DM) + lane; f32x4* orow = (f32x4*)(g_(F.out) + (size_t)m * DM) + 2 * lane; const f32x4* g4 = (const f32x4*)nf + 2 * lane;
; #pragma unroll
;         for (int j = 0; j < 4; ++j) { const u32x4 w = hr[64 * j];
;             orow[128 * j] = (f32x4){bf_lo(w.x), bf_hi(w.x), bf_lo(w.y), bf_hi(w.y)} * rstd * g4[128 * j];
;             orow[128 * j + 1] = (f32x4){bf_lo(w.z), bf_hi(w.z), bf_lo(w.w), bf_hi(w.w)} * rstd * g4[128 * j + 1]; }
;     }
.LBB0_2524:
	s_cmp_lt_i32 s84, 44
	s_cselect_b64 s[0:1], -1, 0
	s_cmp_gt_i32 s85, 43
	s_cselect_b64 s[2:3], -1, 0
	s_and_b64 s[0:1], s[0:1], s[2:3]
	s_and_b64 vcc, exec, s[0:1]
	s_cbranch_vccz .LBB0_2528
	v_readlane_b32 s1, v245, 56
	v_readfirstlane_b32 s0, v0
	s_ashr_i32 s0, s0, 6
	s_lshl_b32 s1, s1, 3
	s_add_i32 s0, s0, s1
	s_mov_b64 s[6:7], 0x26000000
	s_mov_b64 s[2:3], 0x120000
	s_cmpk_gt_i32 s0, 0x1fff
	s_cbranch_scc1 .LBB0_2528
	s_waitcnt vmcnt(0)
	v_and_b32_e32 v14, 63, v0
	v_readlane_b32 s12, v246, 0
	v_lshlrev_b32_e32 v0, 5, v14
	v_mov_b32_e32 v1, 0
	v_readlane_b32 s13, v246, 1
	v_readlane_b32 s18, v246, 6
	v_readlane_b32 s19, v246, 7
	s_mov_b64 s[12:13], 0x1010
	s_ashr_i32 s1, s0, 31
	v_lshl_add_u64 v[2:3], s[18:19], 0, v[0:1]
	v_lshl_add_u64 v[6:7], v[2:3], 0, s[12:13]
	s_mov_b64 s[12:13], 0x1800
	v_lshl_add_u64 v[8:9], v[2:3], 0, s[12:13]
	s_mov_b64 s[12:13], 0x1810
	v_lshl_add_u64 v[10:11], v[2:3], 0, s[12:13]
	s_lshl_b64 s[12:13], s[0:1], 2
	v_readlane_b32 s10, v243, 63
	s_add_u32 s12, s2, s12
	v_readlane_b32 s11, v242, 0
	v_readlane_b32 s14, v246, 2
	v_readlane_b32 s15, v246, 3
	s_addc_u32 s13, s3, s13
	s_ashr_i32 s11, s10, 31
	s_lshl_b64 s[2:3], s[10:11], 2
	s_lshl_b64 s[14:15], s[0:1], 13
	s_add_u32 s8, s52, s14
	s_addc_u32 s9, s53, s15
	s_mov_b64 s[4:5], 0x1000
	v_lshl_add_u64 v[12:13], s[8:9], 0, v[0:1]
	s_waitcnt lgkmcnt(0)
	v_lshl_add_u64 v[4:5], v[2:3], 0, s[4:5]
	v_lshl_add_u64 v[12:13], v[12:13], 0, s[4:5]
	s_lshl_b64 s[4:5], s[10:11], 13
	s_lshl_b64 s[8:9], s[0:1], 12
	s_add_u32 s6, s6, s8
	s_addc_u32 s7, s7, s9
	v_lshlrev_b32_e32 v0, 4, v14
	v_lshl_add_u64 v[14:15], s[6:7], 0, v[0:1]
	s_lshl_b64 s[6:7], s[10:11], 12
	v_mov_b32_e32 v0, 0x8000
	v_mov_b32_e32 v16, 0x10000
	v_mov_b32_e32 v17, 0x18000
	v_mov_b32_e32 v18, 0x20000
	v_mov_b32_e32 v19, 0x28000
	v_mov_b32_e32 v20, 0x30000
	v_mov_b32_e32 v21, 0x38000
	v_mov_b32_e32 v22, 0x358637bd
	v_readlane_b32 s16, v246, 4
	v_readlane_b32 s17, v246, 5
	global_load_dwordx4 v[64:67], v[2:3], off
	global_load_dwordx4 v[68:71], v[2:3], off offset:16
	global_load_dwordx4 v[72:75], v[2:3], off offset:2048
	global_load_dwordx4 v[76:79], v[2:3], off offset:2064
	global_load_dwordx4 v[80:83], v[4:5], off
	global_load_dwordx4 v[84:87], v[6:7], off
	global_load_dwordx4 v[88:91], v[8:9], off
	global_load_dwordx4 v[92:95], v[10:11], off
.LBB0_2527:
	s_add_u32 s8, s54, s12
	s_addc_u32 s9, s55, s13
	v_lshl_add_u64 v[32:33], s[54:55], 0, v[14:15]
	global_load_dword v23, v1, s[8:9]
	global_load_dword v36, v0, s[8:9]
	global_load_dword v37, v16, s[8:9]
	global_load_dword v38, v17, s[8:9]
	global_load_dword v39, v18, s[8:9]
	global_load_dword v40, v19, s[8:9]
	global_load_dword v41, v20, s[8:9]
	global_load_dword v42, v21, s[8:9]
	global_load_dwordx4 v[24:27], v[32:33], off
	global_load_dwordx4 v[44:47], v[32:33], off offset:1024
	global_load_dwordx4 v[48:51], v[32:33], off offset:2048
	global_load_dwordx4 v[52:55], v[32:33], off offset:3072
	s_add_i32 s0, s0, s10
	s_add_u32 s12, s12, s2
	s_addc_u32 s13, s13, s3
	v_lshl_add_u64 v[14:15], v[14:15], 0, s[6:7]
	s_waitcnt vmcnt(11)
	v_add_f32_e32 v23, 0, v23
	s_waitcnt vmcnt(10)
	v_add_f32_e32 v23, v23, v36
	s_waitcnt vmcnt(9)
	v_add_f32_e32 v23, v23, v37
	s_waitcnt vmcnt(8)
	v_add_f32_e32 v23, v23, v38
	s_waitcnt vmcnt(7)
	v_add_f32_e32 v23, v23, v39
	s_waitcnt vmcnt(6)
	v_add_f32_e32 v23, v23, v40
	s_waitcnt vmcnt(5)
	v_add_f32_e32 v23, v23, v41
	s_waitcnt vmcnt(4)
	v_add_f32_e32 v23, v23, v42
	v_fmamk_f32 v23, v23, 0x3a000000, v22
	v_rsq_f32_e32 v36, v23
	s_waitcnt vmcnt(3)
	v_lshlrev_b32_e32 v34, 16, v24
	v_and_b32_e32 v35, 0xffff0000, v24
	v_lshlrev_b32_e32 v60, 16, v25
	v_and_b32_e32 v61, 0xffff0000, v25
	v_pk_mul_f32 v[34:35], v[36:37], v[34:35] op_sel_hi:[0,1]
	v_pk_mul_f32 v[60:61], v[36:37], v[60:61] op_sel_hi:[0,1]
	v_pk_mul_f32 v[56:57], v[64:65], v[34:35]
	v_pk_mul_f32 v[58:59], v[66:67], v[60:61]
	global_store_dwordx4 v[12:13], v[56:59], off offset:-4096
	v_lshlrev_b32_e32 v34, 16, v26
	v_and_b32_e32 v35, 0xffff0000, v26
	v_lshlrev_b32_e32 v60, 16, v27
	v_and_b32_e32 v61, 0xffff0000, v27
	v_pk_mul_f32 v[34:35], v[36:37], v[34:35] op_sel_hi:[0,1]
	v_pk_mul_f32 v[60:61], v[36:37], v[60:61] op_sel_hi:[0,1]
	v_pk_mul_f32 v[96:97], v[68:69], v[34:35]
	v_pk_mul_f32 v[98:99], v[70:71], v[60:61]
	global_store_dwordx4 v[12:13], v[96:99], off offset:-4080
	s_waitcnt vmcnt(4)
	v_lshlrev_b32_e32 v34, 16, v44
	v_and_b32_e32 v35, 0xffff0000, v44
	v_lshlrev_b32_e32 v60, 16, v45
	v_and_b32_e32 v61, 0xffff0000, v45
	v_pk_mul_f32 v[34:35], v[36:37], v[34:35] op_sel_hi:[0,1]
	v_pk_mul_f32 v[60:61], v[36:37], v[60:61] op_sel_hi:[0,1]
	v_pk_mul_f32 v[56:57], v[72:73], v[34:35]
	v_pk_mul_f32 v[58:59], v[74:75], v[60:61]
	global_store_dwordx4 v[12:13], v[56:59], off offset:-2048
	v_lshlrev_b32_e32 v34, 16, v46
	v_and_b32_e32 v35, 0xffff0000, v46
	v_lshlrev_b32_e32 v60, 16, v47
	v_and_b32_e32 v61, 0xffff0000, v47
	v_pk_mul_f32 v[34:35], v[36:37], v[34:35] op_sel_hi:[0,1]
	v_pk_mul_f32 v[60:61], v[36:37], v[60:61] op_sel_hi:[0,1]
	v_pk_mul_f32 v[96:97], v[76:77], v[34:35]
	v_pk_mul_f32 v[98:99], v[78:79], v[60:61]
	global_store_dwordx4 v[12:13], v[96:99], off offset:-2032
	s_waitcnt vmcnt(5)
	v_lshlrev_b32_e32 v34, 16, v48
	v_and_b32_e32 v35, 0xffff0000, v48
	v_lshlrev_b32_e32 v60, 16, v49
	v_and_b32_e32 v61, 0xffff0000, v49
	v_pk_mul_f32 v[34:35], v[36:37], v[34:35] op_sel_hi:[0,1]
	v_pk_mul_f32 v[60:61], v[36:37], v[60:61] op_sel_hi:[0,1]
	v_pk_mul_f32 v[56:57], v[80:81], v[34:35]
	v_pk_mul_f32 v[58:59], v[82:83], v[60:61]
	global_store_dwordx4 v[12:13], v[56:59], off
	v_lshlrev_b32_e32 v34, 16, v50
	v_and_b32_e32 v35, 0xffff0000, v50
	v_lshlrev_b32_e32 v60, 16, v51
	v_and_b32_e32 v61, 0xffff0000, v51
	v_pk_mul_f32 v[34:35], v[36:37], v[34:35] op_sel_hi:[0,1]
	v_pk_mul_f32 v[60:61], v[36:37], v[60:61] op_sel_hi:[0,1]
	v_pk_mul_f32 v[96:97], v[84:85], v[34:35]
	v_pk_mul_f32 v[98:99], v[86:87], v[60:61]
	global_store_dwordx4 v[12:13], v[96:99], off offset:16
	s_waitcnt vmcnt(6)
	v_lshlrev_b32_e32 v34, 16, v52
	v_and_b32_e32 v35, 0xffff0000, v52
	v_lshlrev_b32_e32 v60, 16, v53
	v_and_b32_e32 v61, 0xffff0000, v53
	v_pk_mul_f32 v[34:35], v[36:37], v[34:35] op_sel_hi:[0,1]
	v_pk_mul_f32 v[60:61], v[36:37], v[60:61] op_sel_hi:[0,1]
	v_pk_mul_f32 v[56:57], v[88:89], v[34:35]
	v_pk_mul_f32 v[58:59], v[90:91], v[60:61]
	global_store_dwordx4 v[12:13], v[56:59], off offset:2048
	v_lshlrev_b32_e32 v34, 16, v54
	v_and_b32_e32 v35, 0xffff0000, v54
	v_lshlrev_b32_e32 v60, 16, v55
	v_and_b32_e32 v61, 0xffff0000, v55
	v_pk_mul_f32 v[34:35], v[36:37], v[34:35] op_sel_hi:[0,1]
	v_pk_mul_f32 v[60:61], v[36:37], v[60:61] op_sel_hi:[0,1]
	v_pk_mul_f32 v[96:97], v[92:93], v[34:35]
	v_pk_mul_f32 v[98:99], v[94:95], v[60:61]
	global_store_dwordx4 v[12:13], v[96:99], off offset:2064
	v_lshl_add_u64 v[12:13], v[12:13], 0, s[4:5]
	s_cmpk_lt_i32 s0, 0x2000
	s_cbranch_scc1 .LBB0_2527
